# same optimisations with conservative waits: every wait that has younger stores or mixes LDS-DMA with ordinary loads now waits for everything (vmcnt 0)
# baseline (speedup 1.0000x reference)
.LBB0_419:
	s_or_b64 exec, exec, s[6:7]
	v_mov_b32_e32 v2, v1
	s_barrier
	v_readlane_b32 s6, v243, 2
	v_readfirstlane_b32 s2, v2
	s_ashr_i32 s2, s2, 6
	s_add_i32 s6, s2, s6
	s_mov_b64 s[10:11], s[0:1]
	s_mov_b64 s[12:13], s[0:1]
	s_mov_b64 s[14:15], s[0:1]
	s_cmpk_gt_i32 s6, 0x7fff
	s_cbranch_scc1 .LBB0_422
	s_load_dwordx2 s[16:17], s[10:11], 0x0
	s_load_dwordx2 s[8:9], s[12:13], 0xd8
	s_load_dwordx2 s[18:19], s[14:15], 0xd8
	s_ashr_i32 s7, s6, 31
	s_lshl_b64 s[10:11], s[6:7], 11
	v_and_b32_e32 v7, 63, v2
	v_lshlrev_b32_e32 v3, 2, v2
	s_waitcnt lgkmcnt(0)
	s_add_u32 s10, s18, s10
	v_mov_b32_e32 v5, 0
	v_lshlrev_b32_e32 v4, 3, v7
	s_addc_u32 s11, s19, s11
	v_and_b32_e32 v6, 0xfc, v3
	v_lshl_add_u64 v[2:3], s[10:11], 0, v[4:5]
	s_mov_b64 s[10:11], 0x5800000
	s_ashr_i32 s77, s76, 31
	v_lshl_add_u64 v[2:3], v[2:3], 0, s[10:11]
	s_lshl_b64 s[10:11], s[76:77], 11
	s_lshl_b64 s[12:13], s[6:7], 12
	s_add_u32 s12, s16, s12
	v_lshlrev_b32_e32 v4, 4, v7
	s_addc_u32 s13, s17, s13
	v_or_b32_e32 v8, 0x100, v6
	v_or_b32_e32 v10, 0x200, v6
	v_or_b32_e32 v12, 0x300, v6
	v_lshl_add_u64 v[4:5], s[12:13], 0, v[4:5]
	s_mov_b64 s[12:13], 0xc00
	v_lshl_add_u64 v[4:5], v[4:5], 0, s[12:13]
	s_lshl_b64 s[12:13], s[76:77], 12
	v_lshlrev_b32_e32 v6, 2, v6
	v_lshlrev_b32_e32 v7, 2, v8
	v_lshlrev_b32_e32 v8, 2, v10
	v_lshlrev_b32_e32 v9, 2, v12
	v_mov_b64_e32 v[214:215], v[4:5]
	v_mov_b64_e32 v[222:223], v[2:3]
	v_lshl_add_u64 v[216:217], v[214:215], 0, s[12:13]
	v_lshl_add_u64 v[224:225], v[222:223], 0, s[10:11]
	v_lshl_add_u64 v[218:219], v[216:217], 0, s[12:13]
	v_lshl_add_u64 v[226:227], v[224:225], 0, s[10:11]
	v_lshl_add_u64 v[220:221], v[218:219], 0, s[12:13]
	v_lshl_add_u64 v[228:229], v[226:227], 0, s[10:11]
	v_lshl_add_u64 v[4:5], v[220:221], 0, s[12:13]
	v_lshl_add_u64 v[2:3], v[228:229], 0, s[10:11]
	s_cmpk_gt_i32 s6, 0x3fff
	s_cselect_b32 s2, 0x9000, 0
	s_add_u32 s14, s8, s2
	s_addc_u32 s15, s9, 0
	s_add_u32 s16, s14, 0x1000
	s_addc_u32 s17, s15, 0
	global_load_dwordx4 v[22:25], v[214:215], off offset:-3072 nt
	global_load_dwordx4 v[26:29], v[214:215], off offset:-2048 nt
	global_load_dwordx4 v[30:33], v[214:215], off offset:-1024 nt
	global_load_dwordx4 v[34:37], v[214:215], off offset:0 nt
	global_load_dwordx4 v[38:41], v[216:217], off offset:-3072 nt
	global_load_dwordx4 v[42:45], v[216:217], off offset:-2048 nt
	global_load_dwordx4 v[46:49], v[216:217], off offset:-1024 nt
	global_load_dwordx4 v[50:53], v[216:217], off offset:0 nt
	global_load_dwordx4 v[54:57], v[218:219], off offset:-3072 nt
	global_load_dwordx4 v[58:61], v[218:219], off offset:-2048 nt
	global_load_dwordx4 v[62:65], v[218:219], off offset:-1024 nt
	global_load_dwordx4 v[66:69], v[218:219], off offset:0 nt
	global_load_dwordx4 v[70:73], v[220:221], off offset:-3072 nt
	global_load_dwordx4 v[74:77], v[220:221], off offset:-2048 nt
	global_load_dwordx4 v[78:81], v[220:221], off offset:-1024 nt
	global_load_dwordx4 v[82:85], v[220:221], off offset:0 nt
	global_load_dwordx4 v[150:153], v6, s[16:17]
	global_load_dwordx4 v[154:157], v7, s[16:17]
	global_load_dwordx4 v[158:161], v8, s[16:17]
	global_load_dwordx4 v[162:165], v9, s[16:17]
	global_load_dwordx4 v[166:169], v6, s[14:15]
	global_load_dwordx4 v[170:173], v6, s[14:15] offset:1024
	global_load_dwordx4 v[174:177], v6, s[14:15] offset:2048
	global_load_dwordx4 v[178:181], v6, s[14:15] offset:3072
	s_lshl_b32 s2, s76, 2
	s_add_i32 s6, s6, s2
	v_mov_b64_e32 v[230:231], v[4:5]
	v_mov_b64_e32 v[244:245], v[2:3]
	v_lshl_add_u64 v[232:233], v[230:231], 0, s[12:13]
	v_lshl_add_u64 v[246:247], v[244:245], 0, s[10:11]
	v_lshl_add_u64 v[234:235], v[232:233], 0, s[12:13]
	v_lshl_add_u64 v[248:249], v[246:247], 0, s[10:11]
	v_lshl_add_u64 v[236:237], v[234:235], 0, s[12:13]
	v_lshl_add_u64 v[250:251], v[248:249], 0, s[10:11]
	v_lshl_add_u64 v[4:5], v[236:237], 0, s[12:13]
	v_lshl_add_u64 v[2:3], v[250:251], 0, s[10:11]
	s_cmpk_gt_i32 s6, 0x3fff
	s_cselect_b32 s2, 0x9000, 0
	s_add_u32 s14, s8, s2
	s_addc_u32 s15, s9, 0
	s_add_u32 s16, s14, 0x1000
	s_addc_u32 s17, s15, 0
	global_load_dwordx4 v[86:89], v[230:231], off offset:-3072 nt
	global_load_dwordx4 v[90:93], v[230:231], off offset:-2048 nt
	global_load_dwordx4 v[94:97], v[230:231], off offset:-1024 nt
	global_load_dwordx4 v[98:101], v[230:231], off offset:0 nt
	global_load_dwordx4 v[102:105], v[232:233], off offset:-3072 nt
	global_load_dwordx4 v[106:109], v[232:233], off offset:-2048 nt
	global_load_dwordx4 v[110:113], v[232:233], off offset:-1024 nt
	global_load_dwordx4 v[114:117], v[232:233], off offset:0 nt
	global_load_dwordx4 v[118:121], v[234:235], off offset:-3072 nt
	global_load_dwordx4 v[122:125], v[234:235], off offset:-2048 nt
	global_load_dwordx4 v[126:129], v[234:235], off offset:-1024 nt
	global_load_dwordx4 v[130:133], v[234:235], off offset:0 nt
	global_load_dwordx4 v[134:137], v[236:237], off offset:-3072 nt
	global_load_dwordx4 v[138:141], v[236:237], off offset:-2048 nt
	global_load_dwordx4 v[142:145], v[236:237], off offset:-1024 nt
	global_load_dwordx4 v[146:149], v[236:237], off offset:0 nt
	global_load_dwordx4 v[182:185], v6, s[16:17]
	global_load_dwordx4 v[186:189], v7, s[16:17]
	global_load_dwordx4 v[190:193], v8, s[16:17]
	global_load_dwordx4 v[194:197], v9, s[16:17]
	global_load_dwordx4 v[198:201], v6, s[14:15]
	global_load_dwordx4 v[202:205], v6, s[14:15] offset:1024
	global_load_dwordx4 v[206:209], v6, s[14:15] offset:2048
	global_load_dwordx4 v[210:213], v6, s[14:15] offset:3072
	s_lshl_b32 s2, s76, 2
	s_add_i32 s6, s6, s2
	s_waitcnt vmcnt(24)
	v_pk_add_f32 v[150:151], v[150:151], 1.0 op_sel_hi:[1,0]
	v_pk_add_f32 v[152:153], v[152:153], 1.0 op_sel_hi:[1,0]
	v_pk_add_f32 v[154:155], v[154:155], 1.0 op_sel_hi:[1,0]
	v_pk_add_f32 v[156:157], v[156:157], 1.0 op_sel_hi:[1,0]
	v_pk_add_f32 v[158:159], v[158:159], 1.0 op_sel_hi:[1,0]
	v_pk_add_f32 v[160:161], v[160:161], 1.0 op_sel_hi:[1,0]
	v_pk_add_f32 v[162:163], v[162:163], 1.0 op_sel_hi:[1,0]
	v_pk_add_f32 v[164:165], v[164:165], 1.0 op_sel_hi:[1,0]
	v_pk_fma_f32 v[22:23], v[22:23], v[150:151], v[166:167]
	v_pk_fma_f32 v[24:25], v[24:25], v[152:153], v[168:169]
	v_pk_fma_f32 v[26:27], v[26:27], v[154:155], v[170:171]
	v_pk_fma_f32 v[28:29], v[28:29], v[156:157], v[172:173]
	v_pk_fma_f32 v[30:31], v[30:31], v[158:159], v[174:175]
	v_pk_fma_f32 v[32:33], v[32:33], v[160:161], v[176:177]
	v_pk_fma_f32 v[34:35], v[34:35], v[162:163], v[178:179]
	v_pk_fma_f32 v[36:37], v[36:37], v[164:165], v[180:181]
	v_cvt_pk_bf16_f32 v22, v22, v23
	v_cvt_pk_bf16_f32 v23, v24, v25
	v_cvt_pk_bf16_f32 v26, v26, v27
	v_cvt_pk_bf16_f32 v27, v28, v29
	v_cvt_pk_bf16_f32 v30, v30, v31
	v_cvt_pk_bf16_f32 v31, v32, v33
	v_cvt_pk_bf16_f32 v34, v34, v35
	v_cvt_pk_bf16_f32 v35, v36, v37
	global_store_dwordx2 v[222:223], v[22:23], off
	global_store_dwordx2 v[222:223], v[26:27], off offset:512
	global_store_dwordx2 v[222:223], v[30:31], off offset:1024
	global_store_dwordx2 v[222:223], v[34:35], off offset:1536
	v_pk_fma_f32 v[38:39], v[38:39], v[150:151], v[166:167]
	v_pk_fma_f32 v[40:41], v[40:41], v[152:153], v[168:169]
	v_pk_fma_f32 v[42:43], v[42:43], v[154:155], v[170:171]
	v_pk_fma_f32 v[44:45], v[44:45], v[156:157], v[172:173]
	v_pk_fma_f32 v[46:47], v[46:47], v[158:159], v[174:175]
	v_pk_fma_f32 v[48:49], v[48:49], v[160:161], v[176:177]
	v_pk_fma_f32 v[50:51], v[50:51], v[162:163], v[178:179]
	v_pk_fma_f32 v[52:53], v[52:53], v[164:165], v[180:181]
	v_cvt_pk_bf16_f32 v38, v38, v39
	v_cvt_pk_bf16_f32 v39, v40, v41
	v_cvt_pk_bf16_f32 v42, v42, v43
	v_cvt_pk_bf16_f32 v43, v44, v45
	v_cvt_pk_bf16_f32 v46, v46, v47
	v_cvt_pk_bf16_f32 v47, v48, v49
	v_cvt_pk_bf16_f32 v50, v50, v51
	v_cvt_pk_bf16_f32 v51, v52, v53
	global_store_dwordx2 v[224:225], v[38:39], off
	global_store_dwordx2 v[224:225], v[42:43], off offset:512
	global_store_dwordx2 v[224:225], v[46:47], off offset:1024
	global_store_dwordx2 v[224:225], v[50:51], off offset:1536
	v_pk_fma_f32 v[54:55], v[54:55], v[150:151], v[166:167]
	v_pk_fma_f32 v[56:57], v[56:57], v[152:153], v[168:169]
	v_pk_fma_f32 v[58:59], v[58:59], v[154:155], v[170:171]
	v_pk_fma_f32 v[60:61], v[60:61], v[156:157], v[172:173]
	v_pk_fma_f32 v[62:63], v[62:63], v[158:159], v[174:175]
	v_pk_fma_f32 v[64:65], v[64:65], v[160:161], v[176:177]
	v_pk_fma_f32 v[66:67], v[66:67], v[162:163], v[178:179]
	v_pk_fma_f32 v[68:69], v[68:69], v[164:165], v[180:181]
	v_cvt_pk_bf16_f32 v54, v54, v55
	v_cvt_pk_bf16_f32 v55, v56, v57
	v_cvt_pk_bf16_f32 v58, v58, v59
	v_cvt_pk_bf16_f32 v59, v60, v61
	v_cvt_pk_bf16_f32 v62, v62, v63
	v_cvt_pk_bf16_f32 v63, v64, v65
	v_cvt_pk_bf16_f32 v66, v66, v67
	v_cvt_pk_bf16_f32 v67, v68, v69
	global_store_dwordx2 v[226:227], v[54:55], off
	global_store_dwordx2 v[226:227], v[58:59], off offset:512
	global_store_dwordx2 v[226:227], v[62:63], off offset:1024
	global_store_dwordx2 v[226:227], v[66:67], off offset:1536
	v_pk_fma_f32 v[70:71], v[70:71], v[150:151], v[166:167]
	v_pk_fma_f32 v[72:73], v[72:73], v[152:153], v[168:169]
	v_pk_fma_f32 v[74:75], v[74:75], v[154:155], v[170:171]
	v_pk_fma_f32 v[76:77], v[76:77], v[156:157], v[172:173]
	v_pk_fma_f32 v[78:79], v[78:79], v[158:159], v[174:175]
	v_pk_fma_f32 v[80:81], v[80:81], v[160:161], v[176:177]
	v_pk_fma_f32 v[82:83], v[82:83], v[162:163], v[178:179]
	v_pk_fma_f32 v[84:85], v[84:85], v[164:165], v[180:181]
	v_cvt_pk_bf16_f32 v70, v70, v71
	v_cvt_pk_bf16_f32 v71, v72, v73
	v_cvt_pk_bf16_f32 v74, v74, v75
	v_cvt_pk_bf16_f32 v75, v76, v77
	v_cvt_pk_bf16_f32 v78, v78, v79
	v_cvt_pk_bf16_f32 v79, v80, v81
	v_cvt_pk_bf16_f32 v82, v82, v83
	v_cvt_pk_bf16_f32 v83, v84, v85
	global_store_dwordx2 v[228:229], v[70:71], off
	global_store_dwordx2 v[228:229], v[74:75], off offset:512
	global_store_dwordx2 v[228:229], v[78:79], off offset:1024
	global_store_dwordx2 v[228:229], v[82:83], off offset:1536
	s_waitcnt vmcnt(0)
	v_mov_b64_e32 v[214:215], v[4:5]
	v_mov_b64_e32 v[222:223], v[2:3]
	v_lshl_add_u64 v[216:217], v[214:215], 0, s[12:13]
	v_lshl_add_u64 v[224:225], v[222:223], 0, s[10:11]
	v_lshl_add_u64 v[218:219], v[216:217], 0, s[12:13]
	v_lshl_add_u64 v[226:227], v[224:225], 0, s[10:11]
	v_lshl_add_u64 v[220:221], v[218:219], 0, s[12:13]
	v_lshl_add_u64 v[228:229], v[226:227], 0, s[10:11]
	v_lshl_add_u64 v[4:5], v[220:221], 0, s[12:13]
	v_lshl_add_u64 v[2:3], v[228:229], 0, s[10:11]
	s_cmpk_gt_i32 s6, 0x3fff
	s_cselect_b32 s2, 0x9000, 0
	s_add_u32 s14, s8, s2
	s_addc_u32 s15, s9, 0
	s_add_u32 s16, s14, 0x1000
	s_addc_u32 s17, s15, 0
	global_load_dwordx4 v[22:25], v[214:215], off offset:-3072 nt
	global_load_dwordx4 v[26:29], v[214:215], off offset:-2048 nt
	global_load_dwordx4 v[30:33], v[214:215], off offset:-1024 nt
	global_load_dwordx4 v[34:37], v[214:215], off offset:0 nt
	global_load_dwordx4 v[38:41], v[216:217], off offset:-3072 nt
	global_load_dwordx4 v[42:45], v[216:217], off offset:-2048 nt
	global_load_dwordx4 v[46:49], v[216:217], off offset:-1024 nt
	global_load_dwordx4 v[50:53], v[216:217], off offset:0 nt
	global_load_dwordx4 v[54:57], v[218:219], off offset:-3072 nt
	global_load_dwordx4 v[58:61], v[218:219], off offset:-2048 nt
	global_load_dwordx4 v[62:65], v[218:219], off offset:-1024 nt
	global_load_dwordx4 v[66:69], v[218:219], off offset:0 nt
	global_load_dwordx4 v[70:73], v[220:221], off offset:-3072 nt
	global_load_dwordx4 v[74:77], v[220:221], off offset:-2048 nt
	global_load_dwordx4 v[78:81], v[220:221], off offset:-1024 nt
	global_load_dwordx4 v[82:85], v[220:221], off offset:0 nt
	global_load_dwordx4 v[150:153], v6, s[16:17]
	global_load_dwordx4 v[154:157], v7, s[16:17]
	global_load_dwordx4 v[158:161], v8, s[16:17]
	global_load_dwordx4 v[162:165], v9, s[16:17]
	global_load_dwordx4 v[166:169], v6, s[14:15]
	global_load_dwordx4 v[170:173], v6, s[14:15] offset:1024
	global_load_dwordx4 v[174:177], v6, s[14:15] offset:2048
	global_load_dwordx4 v[178:181], v6, s[14:15] offset:3072
	s_lshl_b32 s2, s76, 2
	s_add_i32 s6, s6, s2
	v_pk_add_f32 v[182:183], v[182:183], 1.0 op_sel_hi:[1,0]
	v_pk_add_f32 v[184:185], v[184:185], 1.0 op_sel_hi:[1,0]
	v_pk_add_f32 v[186:187], v[186:187], 1.0 op_sel_hi:[1,0]
	v_pk_add_f32 v[188:189], v[188:189], 1.0 op_sel_hi:[1,0]
	v_pk_add_f32 v[190:191], v[190:191], 1.0 op_sel_hi:[1,0]
	v_pk_add_f32 v[192:193], v[192:193], 1.0 op_sel_hi:[1,0]
	v_pk_add_f32 v[194:195], v[194:195], 1.0 op_sel_hi:[1,0]
	v_pk_add_f32 v[196:197], v[196:197], 1.0 op_sel_hi:[1,0]
	v_pk_fma_f32 v[86:87], v[86:87], v[182:183], v[198:199]
	v_pk_fma_f32 v[88:89], v[88:89], v[184:185], v[200:201]
	v_pk_fma_f32 v[90:91], v[90:91], v[186:187], v[202:203]
	v_pk_fma_f32 v[92:93], v[92:93], v[188:189], v[204:205]
	v_pk_fma_f32 v[94:95], v[94:95], v[190:191], v[206:207]
	v_pk_fma_f32 v[96:97], v[96:97], v[192:193], v[208:209]
	v_pk_fma_f32 v[98:99], v[98:99], v[194:195], v[210:211]
	v_pk_fma_f32 v[100:101], v[100:101], v[196:197], v[212:213]
	v_cvt_pk_bf16_f32 v86, v86, v87
	v_cvt_pk_bf16_f32 v87, v88, v89
	v_cvt_pk_bf16_f32 v90, v90, v91
	v_cvt_pk_bf16_f32 v91, v92, v93
	v_cvt_pk_bf16_f32 v94, v94, v95
	v_cvt_pk_bf16_f32 v95, v96, v97
	v_cvt_pk_bf16_f32 v98, v98, v99
	v_cvt_pk_bf16_f32 v99, v100, v101
	global_store_dwordx2 v[244:245], v[86:87], off
	global_store_dwordx2 v[244:245], v[90:91], off offset:512
	global_store_dwordx2 v[244:245], v[94:95], off offset:1024
	global_store_dwordx2 v[244:245], v[98:99], off offset:1536
	v_pk_fma_f32 v[102:103], v[102:103], v[182:183], v[198:199]
	v_pk_fma_f32 v[104:105], v[104:105], v[184:185], v[200:201]
	v_pk_fma_f32 v[106:107], v[106:107], v[186:187], v[202:203]
	v_pk_fma_f32 v[108:109], v[108:109], v[188:189], v[204:205]
	v_pk_fma_f32 v[110:111], v[110:111], v[190:191], v[206:207]
	v_pk_fma_f32 v[112:113], v[112:113], v[192:193], v[208:209]
	v_pk_fma_f32 v[114:115], v[114:115], v[194:195], v[210:211]
	v_pk_fma_f32 v[116:117], v[116:117], v[196:197], v[212:213]
	v_cvt_pk_bf16_f32 v102, v102, v103
	v_cvt_pk_bf16_f32 v103, v104, v105
	v_cvt_pk_bf16_f32 v106, v106, v107
	v_cvt_pk_bf16_f32 v107, v108, v109
	v_cvt_pk_bf16_f32 v110, v110, v111
	v_cvt_pk_bf16_f32 v111, v112, v113
	v_cvt_pk_bf16_f32 v114, v114, v115
	v_cvt_pk_bf16_f32 v115, v116, v117
	global_store_dwordx2 v[246:247], v[102:103], off
	global_store_dwordx2 v[246:247], v[106:107], off offset:512
	global_store_dwordx2 v[246:247], v[110:111], off offset:1024
	global_store_dwordx2 v[246:247], v[114:115], off offset:1536
	v_pk_fma_f32 v[118:119], v[118:119], v[182:183], v[198:199]
	v_pk_fma_f32 v[120:121], v[120:121], v[184:185], v[200:201]
	v_pk_fma_f32 v[122:123], v[122:123], v[186:187], v[202:203]
	v_pk_fma_f32 v[124:125], v[124:125], v[188:189], v[204:205]
	v_pk_fma_f32 v[126:127], v[126:127], v[190:191], v[206:207]
	v_pk_fma_f32 v[128:129], v[128:129], v[192:193], v[208:209]
	v_pk_fma_f32 v[130:131], v[130:131], v[194:195], v[210:211]
	v_pk_fma_f32 v[132:133], v[132:133], v[196:197], v[212:213]
	v_cvt_pk_bf16_f32 v118, v118, v119
	v_cvt_pk_bf16_f32 v119, v120, v121
	v_cvt_pk_bf16_f32 v122, v122, v123
	v_cvt_pk_bf16_f32 v123, v124, v125
	v_cvt_pk_bf16_f32 v126, v126, v127
	v_cvt_pk_bf16_f32 v127, v128, v129
	v_cvt_pk_bf16_f32 v130, v130, v131
	v_cvt_pk_bf16_f32 v131, v132, v133
	global_store_dwordx2 v[248:249], v[118:119], off
	global_store_dwordx2 v[248:249], v[122:123], off offset:512
	global_store_dwordx2 v[248:249], v[126:127], off offset:1024
	global_store_dwordx2 v[248:249], v[130:131], off offset:1536
	v_pk_fma_f32 v[134:135], v[134:135], v[182:183], v[198:199]
	v_pk_fma_f32 v[136:137], v[136:137], v[184:185], v[200:201]
	v_pk_fma_f32 v[138:139], v[138:139], v[186:187], v[202:203]
	v_pk_fma_f32 v[140:141], v[140:141], v[188:189], v[204:205]
	v_pk_fma_f32 v[142:143], v[142:143], v[190:191], v[206:207]
	v_pk_fma_f32 v[144:145], v[144:145], v[192:193], v[208:209]
	v_pk_fma_f32 v[146:147], v[146:147], v[194:195], v[210:211]
	v_pk_fma_f32 v[148:149], v[148:149], v[196:197], v[212:213]
	v_cvt_pk_bf16_f32 v134, v134, v135
	v_cvt_pk_bf16_f32 v135, v136, v137
	v_cvt_pk_bf16_f32 v138, v138, v139
	v_cvt_pk_bf16_f32 v139, v140, v141
	v_cvt_pk_bf16_f32 v142, v142, v143
	v_cvt_pk_bf16_f32 v143, v144, v145
	v_cvt_pk_bf16_f32 v146, v146, v147
	v_cvt_pk_bf16_f32 v147, v148, v149
	global_store_dwordx2 v[250:251], v[134:135], off
	global_store_dwordx2 v[250:251], v[138:139], off offset:512
	global_store_dwordx2 v[250:251], v[142:143], off offset:1024
	global_store_dwordx2 v[250:251], v[146:147], off offset:1536
	s_waitcnt vmcnt(0)
	v_mov_b64_e32 v[230:231], v[4:5]
	v_mov_b64_e32 v[244:245], v[2:3]
	v_lshl_add_u64 v[232:233], v[230:231], 0, s[12:13]
	v_lshl_add_u64 v[246:247], v[244:245], 0, s[10:11]
	v_lshl_add_u64 v[234:235], v[232:233], 0, s[12:13]
	v_lshl_add_u64 v[248:249], v[246:247], 0, s[10:11]
	v_lshl_add_u64 v[236:237], v[234:235], 0, s[12:13]
	v_lshl_add_u64 v[250:251], v[248:249], 0, s[10:11]
	v_lshl_add_u64 v[4:5], v[236:237], 0, s[12:13]
	v_lshl_add_u64 v[2:3], v[250:251], 0, s[10:11]
	s_cmpk_gt_i32 s6, 0x3fff
	s_cselect_b32 s2, 0x9000, 0
	s_add_u32 s14, s8, s2
	s_addc_u32 s15, s9, 0
	s_add_u32 s16, s14, 0x1000
	s_addc_u32 s17, s15, 0
	global_load_dwordx4 v[86:89], v[230:231], off offset:-3072 nt
	global_load_dwordx4 v[90:93], v[230:231], off offset:-2048 nt
	global_load_dwordx4 v[94:97], v[230:231], off offset:-1024 nt
	global_load_dwordx4 v[98:101], v[230:231], off offset:0 nt
	global_load_dwordx4 v[102:105], v[232:233], off offset:-3072 nt
	global_load_dwordx4 v[106:109], v[232:233], off offset:-2048 nt
	global_load_dwordx4 v[110:113], v[232:233], off offset:-1024 nt
	global_load_dwordx4 v[114:117], v[232:233], off offset:0 nt
	global_load_dwordx4 v[118:121], v[234:235], off offset:-3072 nt
	global_load_dwordx4 v[122:125], v[234:235], off offset:-2048 nt
	global_load_dwordx4 v[126:129], v[234:235], off offset:-1024 nt
	global_load_dwordx4 v[130:133], v[234:235], off offset:0 nt
	global_load_dwordx4 v[134:137], v[236:237], off offset:-3072 nt
	global_load_dwordx4 v[138:141], v[236:237], off offset:-2048 nt
	global_load_dwordx4 v[142:145], v[236:237], off offset:-1024 nt
	global_load_dwordx4 v[146:149], v[236:237], off offset:0 nt
	global_load_dwordx4 v[182:185], v6, s[16:17]
	global_load_dwordx4 v[186:189], v7, s[16:17]
	global_load_dwordx4 v[190:193], v8, s[16:17]
	global_load_dwordx4 v[194:197], v9, s[16:17]
	global_load_dwordx4 v[198:201], v6, s[14:15]
	global_load_dwordx4 v[202:205], v6, s[14:15] offset:1024
	global_load_dwordx4 v[206:209], v6, s[14:15] offset:2048
	global_load_dwordx4 v[210:213], v6, s[14:15] offset:3072
	s_lshl_b32 s2, s76, 2
	s_add_i32 s6, s6, s2
	v_pk_add_f32 v[150:151], v[150:151], 1.0 op_sel_hi:[1,0]
	v_pk_add_f32 v[152:153], v[152:153], 1.0 op_sel_hi:[1,0]
	v_pk_add_f32 v[154:155], v[154:155], 1.0 op_sel_hi:[1,0]
	v_pk_add_f32 v[156:157], v[156:157], 1.0 op_sel_hi:[1,0]
	v_pk_add_f32 v[158:159], v[158:159], 1.0 op_sel_hi:[1,0]
	v_pk_add_f32 v[160:161], v[160:161], 1.0 op_sel_hi:[1,0]
	v_pk_add_f32 v[162:163], v[162:163], 1.0 op_sel_hi:[1,0]
	v_pk_add_f32 v[164:165], v[164:165], 1.0 op_sel_hi:[1,0]
	v_pk_fma_f32 v[22:23], v[22:23], v[150:151], v[166:167]
	v_pk_fma_f32 v[24:25], v[24:25], v[152:153], v[168:169]
	v_pk_fma_f32 v[26:27], v[26:27], v[154:155], v[170:171]
	v_pk_fma_f32 v[28:29], v[28:29], v[156:157], v[172:173]
	v_pk_fma_f32 v[30:31], v[30:31], v[158:159], v[174:175]
	v_pk_fma_f32 v[32:33], v[32:33], v[160:161], v[176:177]
	v_pk_fma_f32 v[34:35], v[34:35], v[162:163], v[178:179]
	v_pk_fma_f32 v[36:37], v[36:37], v[164:165], v[180:181]
	v_cvt_pk_bf16_f32 v22, v22, v23
	v_cvt_pk_bf16_f32 v23, v24, v25
	v_cvt_pk_bf16_f32 v26, v26, v27
	v_cvt_pk_bf16_f32 v27, v28, v29
	v_cvt_pk_bf16_f32 v30, v30, v31
	v_cvt_pk_bf16_f32 v31, v32, v33
	v_cvt_pk_bf16_f32 v34, v34, v35
	v_cvt_pk_bf16_f32 v35, v36, v37
	global_store_dwordx2 v[222:223], v[22:23], off
	global_store_dwordx2 v[222:223], v[26:27], off offset:512
	global_store_dwordx2 v[222:223], v[30:31], off offset:1024
	global_store_dwordx2 v[222:223], v[34:35], off offset:1536
	v_pk_fma_f32 v[38:39], v[38:39], v[150:151], v[166:167]
	v_pk_fma_f32 v[40:41], v[40:41], v[152:153], v[168:169]
	v_pk_fma_f32 v[42:43], v[42:43], v[154:155], v[170:171]
	v_pk_fma_f32 v[44:45], v[44:45], v[156:157], v[172:173]
	v_pk_fma_f32 v[46:47], v[46:47], v[158:159], v[174:175]
	v_pk_fma_f32 v[48:49], v[48:49], v[160:161], v[176:177]
	v_pk_fma_f32 v[50:51], v[50:51], v[162:163], v[178:179]
	v_pk_fma_f32 v[52:53], v[52:53], v[164:165], v[180:181]
	v_cvt_pk_bf16_f32 v38, v38, v39
	v_cvt_pk_bf16_f32 v39, v40, v41
	v_cvt_pk_bf16_f32 v42, v42, v43
	v_cvt_pk_bf16_f32 v43, v44, v45
	v_cvt_pk_bf16_f32 v46, v46, v47
	v_cvt_pk_bf16_f32 v47, v48, v49
	v_cvt_pk_bf16_f32 v50, v50, v51
	v_cvt_pk_bf16_f32 v51, v52, v53
	global_store_dwordx2 v[224:225], v[38:39], off
	global_store_dwordx2 v[224:225], v[42:43], off offset:512
	global_store_dwordx2 v[224:225], v[46:47], off offset:1024
	global_store_dwordx2 v[224:225], v[50:51], off offset:1536
	v_pk_fma_f32 v[54:55], v[54:55], v[150:151], v[166:167]
	v_pk_fma_f32 v[56:57], v[56:57], v[152:153], v[168:169]
	v_pk_fma_f32 v[58:59], v[58:59], v[154:155], v[170:171]
	v_pk_fma_f32 v[60:61], v[60:61], v[156:157], v[172:173]
	v_pk_fma_f32 v[62:63], v[62:63], v[158:159], v[174:175]
	v_pk_fma_f32 v[64:65], v[64:65], v[160:161], v[176:177]
	v_pk_fma_f32 v[66:67], v[66:67], v[162:163], v[178:179]
	v_pk_fma_f32 v[68:69], v[68:69], v[164:165], v[180:181]
	v_cvt_pk_bf16_f32 v54, v54, v55
	v_cvt_pk_bf16_f32 v55, v56, v57
	v_cvt_pk_bf16_f32 v58, v58, v59
	v_cvt_pk_bf16_f32 v59, v60, v61
	v_cvt_pk_bf16_f32 v62, v62, v63
	v_cvt_pk_bf16_f32 v63, v64, v65
	v_cvt_pk_bf16_f32 v66, v66, v67
	v_cvt_pk_bf16_f32 v67, v68, v69
	global_store_dwordx2 v[226:227], v[54:55], off
	global_store_dwordx2 v[226:227], v[58:59], off offset:512
	global_store_dwordx2 v[226:227], v[62:63], off offset:1024
	global_store_dwordx2 v[226:227], v[66:67], off offset:1536
	v_pk_fma_f32 v[70:71], v[70:71], v[150:151], v[166:167]
	v_pk_fma_f32 v[72:73], v[72:73], v[152:153], v[168:169]
	v_pk_fma_f32 v[74:75], v[74:75], v[154:155], v[170:171]
	v_pk_fma_f32 v[76:77], v[76:77], v[156:157], v[172:173]
	v_pk_fma_f32 v[78:79], v[78:79], v[158:159], v[174:175]
	v_pk_fma_f32 v[80:81], v[80:81], v[160:161], v[176:177]
	v_pk_fma_f32 v[82:83], v[82:83], v[162:163], v[178:179]
	v_pk_fma_f32 v[84:85], v[84:85], v[164:165], v[180:181]
	v_cvt_pk_bf16_f32 v70, v70, v71
	v_cvt_pk_bf16_f32 v71, v72, v73
	v_cvt_pk_bf16_f32 v74, v74, v75
	v_cvt_pk_bf16_f32 v75, v76, v77
	v_cvt_pk_bf16_f32 v78, v78, v79
	v_cvt_pk_bf16_f32 v79, v80, v81
	v_cvt_pk_bf16_f32 v82, v82, v83
	v_cvt_pk_bf16_f32 v83, v84, v85
	global_store_dwordx2 v[228:229], v[70:71], off
	global_store_dwordx2 v[228:229], v[74:75], off offset:512
	global_store_dwordx2 v[228:229], v[78:79], off offset:1024
	global_store_dwordx2 v[228:229], v[82:83], off offset:1536
	s_waitcnt vmcnt(0)
	v_pk_add_f32 v[182:183], v[182:183], 1.0 op_sel_hi:[1,0]
	v_pk_add_f32 v[184:185], v[184:185], 1.0 op_sel_hi:[1,0]
	v_pk_add_f32 v[186:187], v[186:187], 1.0 op_sel_hi:[1,0]
	v_pk_add_f32 v[188:189], v[188:189], 1.0 op_sel_hi:[1,0]
	v_pk_add_f32 v[190:191], v[190:191], 1.0 op_sel_hi:[1,0]
	v_pk_add_f32 v[192:193], v[192:193], 1.0 op_sel_hi:[1,0]
	v_pk_add_f32 v[194:195], v[194:195], 1.0 op_sel_hi:[1,0]
	v_pk_add_f32 v[196:197], v[196:197], 1.0 op_sel_hi:[1,0]
	v_pk_fma_f32 v[86:87], v[86:87], v[182:183], v[198:199]
	v_pk_fma_f32 v[88:89], v[88:89], v[184:185], v[200:201]
	v_pk_fma_f32 v[90:91], v[90:91], v[186:187], v[202:203]
	v_pk_fma_f32 v[92:93], v[92:93], v[188:189], v[204:205]
	v_pk_fma_f32 v[94:95], v[94:95], v[190:191], v[206:207]
	v_pk_fma_f32 v[96:97], v[96:97], v[192:193], v[208:209]
	v_pk_fma_f32 v[98:99], v[98:99], v[194:195], v[210:211]
	v_pk_fma_f32 v[100:101], v[100:101], v[196:197], v[212:213]
	v_cvt_pk_bf16_f32 v86, v86, v87
	v_cvt_pk_bf16_f32 v87, v88, v89
	v_cvt_pk_bf16_f32 v90, v90, v91
	v_cvt_pk_bf16_f32 v91, v92, v93
	v_cvt_pk_bf16_f32 v94, v94, v95
	v_cvt_pk_bf16_f32 v95, v96, v97
	v_cvt_pk_bf16_f32 v98, v98, v99
	v_cvt_pk_bf16_f32 v99, v100, v101
	global_store_dwordx2 v[244:245], v[86:87], off
	global_store_dwordx2 v[244:245], v[90:91], off offset:512
	global_store_dwordx2 v[244:245], v[94:95], off offset:1024
	global_store_dwordx2 v[244:245], v[98:99], off offset:1536
	v_pk_fma_f32 v[102:103], v[102:103], v[182:183], v[198:199]
	v_pk_fma_f32 v[104:105], v[104:105], v[184:185], v[200:201]
	v_pk_fma_f32 v[106:107], v[106:107], v[186:187], v[202:203]
	v_pk_fma_f32 v[108:109], v[108:109], v[188:189], v[204:205]
	v_pk_fma_f32 v[110:111], v[110:111], v[190:191], v[206:207]
	v_pk_fma_f32 v[112:113], v[112:113], v[192:193], v[208:209]
	v_pk_fma_f32 v[114:115], v[114:115], v[194:195], v[210:211]
	v_pk_fma_f32 v[116:117], v[116:117], v[196:197], v[212:213]
	v_cvt_pk_bf16_f32 v102, v102, v103
	v_cvt_pk_bf16_f32 v103, v104, v105
	v_cvt_pk_bf16_f32 v106, v106, v107
	v_cvt_pk_bf16_f32 v107, v108, v109
	v_cvt_pk_bf16_f32 v110, v110, v111
	v_cvt_pk_bf16_f32 v111, v112, v113
	v_cvt_pk_bf16_f32 v114, v114, v115
	v_cvt_pk_bf16_f32 v115, v116, v117
	global_store_dwordx2 v[246:247], v[102:103], off
	global_store_dwordx2 v[246:247], v[106:107], off offset:512
	global_store_dwordx2 v[246:247], v[110:111], off offset:1024
	global_store_dwordx2 v[246:247], v[114:115], off offset:1536
	v_pk_fma_f32 v[118:119], v[118:119], v[182:183], v[198:199]
	v_pk_fma_f32 v[120:121], v[120:121], v[184:185], v[200:201]
	v_pk_fma_f32 v[122:123], v[122:123], v[186:187], v[202:203]
	v_pk_fma_f32 v[124:125], v[124:125], v[188:189], v[204:205]
	v_pk_fma_f32 v[126:127], v[126:127], v[190:191], v[206:207]
	v_pk_fma_f32 v[128:129], v[128:129], v[192:193], v[208:209]
	v_pk_fma_f32 v[130:131], v[130:131], v[194:195], v[210:211]
	v_pk_fma_f32 v[132:133], v[132:133], v[196:197], v[212:213]
	v_cvt_pk_bf16_f32 v118, v118, v119
	v_cvt_pk_bf16_f32 v119, v120, v121
	v_cvt_pk_bf16_f32 v122, v122, v123
	v_cvt_pk_bf16_f32 v123, v124, v125
	v_cvt_pk_bf16_f32 v126, v126, v127
	v_cvt_pk_bf16_f32 v127, v128, v129
	v_cvt_pk_bf16_f32 v130, v130, v131
	v_cvt_pk_bf16_f32 v131, v132, v133
	global_store_dwordx2 v[248:249], v[118:119], off
	global_store_dwordx2 v[248:249], v[122:123], off offset:512
	global_store_dwordx2 v[248:249], v[126:127], off offset:1024
	global_store_dwordx2 v[248:249], v[130:131], off offset:1536
	v_pk_fma_f32 v[134:135], v[134:135], v[182:183], v[198:199]
	v_pk_fma_f32 v[136:137], v[136:137], v[184:185], v[200:201]
	v_pk_fma_f32 v[138:139], v[138:139], v[186:187], v[202:203]
	v_pk_fma_f32 v[140:141], v[140:141], v[188:189], v[204:205]
	v_pk_fma_f32 v[142:143], v[142:143], v[190:191], v[206:207]
	v_pk_fma_f32 v[144:145], v[144:145], v[192:193], v[208:209]
	v_pk_fma_f32 v[146:147], v[146:147], v[194:195], v[210:211]
	v_pk_fma_f32 v[148:149], v[148:149], v[196:197], v[212:213]
	v_cvt_pk_bf16_f32 v134, v134, v135
	v_cvt_pk_bf16_f32 v135, v136, v137
	v_cvt_pk_bf16_f32 v138, v138, v139
	v_cvt_pk_bf16_f32 v139, v140, v141
	v_cvt_pk_bf16_f32 v142, v142, v143
	v_cvt_pk_bf16_f32 v143, v144, v145
	v_cvt_pk_bf16_f32 v146, v146, v147
	v_cvt_pk_bf16_f32 v147, v148, v149
	global_store_dwordx2 v[250:251], v[134:135], off
	global_store_dwordx2 v[250:251], v[138:139], off offset:512
	global_store_dwordx2 v[250:251], v[142:143], off offset:1024
	global_store_dwordx2 v[250:251], v[146:147], off offset:1536

lnd_have:
	s_mov_b32 s38, 1
	v_readlane_b32 s77, v242, 11
	s_add_i32 s92, s10, s77
	s_add_i32 s93, s76, s92
	s_cmp_lt_i32 s93, 0x8000
	s_cselect_b32 s93, s93, s92
	s_ashr_i32 s97, s93, 31
	s_mov_b32 s96, s93
	s_lshl_b64 s[98:99], s[96:97], 12
	v_lshl_add_u64 v[244:245], v[2:3], 0, s[66:67]
	v_lshl_add_u64 v[246:247], v[28:29], 0, s[98:99]
	s_lshl_b64 s[98:99], s[96:97], 11
	v_lshl_add_u64 v[248:249], v[252:253], 0, s[68:69]
	v_lshl_add_u64 v[252:253], v[30:31], 0, v[42:43]
	v_lshl_add_u64 v[252:253], v[252:253], 0, s[98:99]
	s_waitcnt vmcnt(0)
	ds_read_b128 v[44:47], v250 offset:0
	ds_read_b128 v[48:51], v250 offset:4096
	ds_read_b64 v[62:63], v251 offset:8192
	ds_read_b64 v[72:73], v251 offset:10240
	ds_read_b128 v[76:79], v250 offset:1024
	ds_read_b128 v[20:23], v250 offset:5120
	ds_read_b64 v[80:81], v251 offset:8704
	ds_read_b64 v[54:55], v251 offset:10752
	ds_read_b128 v[16:19], v250 offset:2048
	ds_read_b128 v[12:15], v250 offset:6144
	ds_read_b64 v[52:53], v251 offset:9216
	ds_read_b64 v[60:61], v251 offset:11264
	ds_read_b128 v[6:9], v250 offset:3072
	ds_read_b128 v[2:5], v250 offset:7168
	ds_read_b64 v[68:69], v251 offset:9728
	ds_read_b64 v[64:65], v251 offset:11776
	global_load_dwordx4 v[190:193], v[70:71], off
	global_load_dwordx4 v[194:197], v[70:71], off offset:1024
	global_load_dwordx4 v[198:201], v[70:71], off offset:2048
	global_load_dwordx4 v[214:217], v[70:71], off offset:3072
	global_load_dwordx4 v[218:221], v[236:237], off
	global_load_dwordx4 v[222:225], v[236:237], off offset:1024
	global_load_dwordx4 v[226:229], v[236:237], off offset:2048
	global_load_dwordx4 v[230:233], v[236:237], off offset:3072
	global_load_dwordx4 v[84:87], v[34:35], off
	global_load_dwordx4 v[88:91], v[34:35], off offset:1024
	global_load_dwordx4 v[92:95], v[34:35], off offset:2048
	global_load_dwordx4 v[96:99], v[34:35], off offset:3072
	global_load_dwordx4 v[100:103], v[36:37], off
	global_load_dwordx4 v[104:107], v[36:37], off offset:1024
	global_load_dwordx4 v[108:111], v[36:37], off offset:2048
	global_load_dwordx4 v[112:115], v[36:37], off offset:3072
	global_load_dwordx4 v[116:119], v234, s[22:23]
	global_load_dwordx4 v[120:123], v27, s[22:23]
	global_load_dwordx4 v[124:127], v74, s[22:23]
	global_load_dwordx4 v[128:131], v75, s[22:23]
	global_load_dwordx4 v[132:135], v234, s[20:21]
	global_load_dwordx4 v[136:139], v234, s[20:21] offset:1024
	global_load_dwordx4 v[140:143], v234, s[20:21] offset:2048
	global_load_dwordx4 v[144:147], v234, s[20:21] offset:3072
	global_load_dwordx4 v[148:151], v234, s[54:55]
	global_load_dwordx4 v[152:155], v27, s[54:55]
	global_load_dwordx4 v[156:159], v74, s[54:55]
	global_load_dwordx4 v[160:163], v75, s[54:55]
	global_load_dwordx4 v[164:167], v234, s[50:51]
	global_load_dwordx4 v[168:171], v234, s[50:51] offset:1024
	global_load_dwordx4 v[182:185], v234, s[50:51] offset:2048
	global_load_dwordx4 v[186:189], v234, s[50:51] offset:3072
	v_mov_b32_e32 v25, v24
	s_waitcnt vmcnt(0) lgkmcnt(0)
	s_cmpk_gt_i32 s92, 0x7fff
	s_cbranch_scc1 lnd_join
	s_mov_b32 m0, s32
	s_nop 0
	global_load_lds_dwordx4 v[244:245], off nt
	global_load_lds_dwordx4 v[244:245], off offset:1024 nt
	global_load_lds_dwordx4 v[244:245], off offset:2048 nt
	global_load_lds_dwordx4 v[244:245], off offset:3072 nt
	s_add_i32 m0, s32, 0x1000
	s_nop 0
	global_load_lds_dwordx4 v[246:247], off nt
	global_load_lds_dwordx4 v[246:247], off offset:1024 nt
	global_load_lds_dwordx4 v[246:247], off offset:2048 nt
	global_load_lds_dwordx4 v[246:247], off offset:3072 nt
	s_add_i32 m0, s32, 0x2000
	s_nop 0
	global_load_lds_dwordx4 v[248:249], off nt
	global_load_lds_dwordx4 v[248:249], off offset:1024 nt
	s_add_i32 m0, s32, 0x2800
	s_nop 0
	global_load_lds_dwordx4 v[252:253], off nt
	global_load_lds_dwordx4 v[252:253], off offset:1024 nt
